# B3: redundant workgroup barrier at the end of the ff1 and w_in GEMM phases removed (grid barrier entry follows immediately); on top of A2
# speedup vs baseline: 1.0010x; 1.0010x over previous
.LBB0_272:
	s_waitcnt vmcnt(0)
	s_mov_b64 s[98:99], s[96:97]
	v_readlane_b32 s96, v255, 40
	v_readlane_b32 s64, v255, 42
	v_readlane_b32 s66, v255, 44
	s_mov_b32 s70, 0x3c1c381e
	v_readlane_b32 s97, v255, 41
	v_readlane_b32 s65, v255, 43
	v_readlane_b32 s67, v255, 45
	s_mov_b32 s71, 0x3fe1feb3
	s_mov_b32 s77, 0x5f00000
	s_nop 0

.LBB0_515:
	s_waitcnt vmcnt(0)
	v_readlane_b32 s96, v255, 40
	v_readlane_b32 s64, v255, 42
	v_readlane_b32 s66, v255, 44
	s_mov_b32 s70, 0x3c1c381e
	v_readlane_b32 s97, v255, 41
	v_readlane_b32 s65, v255, 43
	v_readlane_b32 s67, v255, 45
	s_mov_b32 s71, 0x3fe1feb3
	s_mov_b32 s77, 0x5f00000
	s_mov_b64 s[22:23], s[90:91]
	s_nop 0
